# work-queue atomic for the next unit no longer waited at unit start; its result is stored to the LDS slot at unit end
# baseline (speedup 1.0000x reference)
; #define LAS __attribute__((address_space(3)))
; __device__ __forceinline__ unsigned pk2(float lo, float hi) { f32x2_t v = {lo, hi}; bf16x2_t b = __builtin_convertvector(v, bf16x2_t); return __builtin_bit_cast(unsigned, b); }
; __device__ __forceinline__ void attn_unit(unsigned char* ws, LAS unsigned char* lds, int b, int g, int c, const int tid) {
;     ...
;       for (int i = 0; i < 16; ++i) { st.o0[i] = outl[i * 512] + st.o0[i] * sc; st.o1[i] = outl[(16 + i) * 512] + st.o1[i] * sc; } }
;     bf16_t* op = (bf16_t*)(ws + WS_ATT) + row * 1024 + head * 64 + 4 * h;
; #pragma unroll
;     for (int gi = 0; gi < 4; ++gi) {
;         u32x2 w0; w0.x = pk2(st.o0[4 * gi], st.o0[4 * gi + 1]); w0.y = pk2(st.o0[4 * gi + 2], st.o0[4 * gi + 3]); *(u32x2*)(op + 8 * gi) = w0;
;         u32x2 w1; w1.x = pk2(st.o1[4 * gi], st.o1[4 * gi + 1]); w1.y = pk2(st.o1[4 * gi + 2], st.o1[4 * gi + 3]); *(u32x2*)(op + 32 + 8 * gi) = w1;
;     }
; }
; __device__ __forceinline__ void attn_phase(unsigned char* ws, LAS unsigned char* lds, const int tid, const int bid, const int l) {
;     unsigned* ctr = (unsigned*)(ws + WS_CTL) + 3584 + 64 * l;
;     volatile LAS int* slot = (volatile LAS int*)(lds + LDS_MISC + 48);
;     if (tid == 0) slot[0] = (int)__hip_atomic_fetch_add(ctr, 1u, __ATOMIC_RELAXED, __HIP_MEMORY_SCOPE_AGENT);
;     __syncthreads();
;     int u = slot[0];
;     while (u < 1024) {
;         __syncthreads();
;         if (tid == 0) slot[0] = (int)__hip_atomic_fetch_add(ctr, 1u, __ATOMIC_RELAXED, __HIP_MEMORY_SCOPE_AGENT);
.LBB0_131:
	s_or_b64 exec, exec, s[4:5]
	ds_read2st64_b32 v[36:37], v199 offset1:8
	ds_read2st64_b32 v[38:39], v199 offset0:128 offset1:136
	ds_read2st64_b32 v[40:41], v199 offset0:16 offset1:24
	ds_read2st64_b32 v[42:43], v199 offset0:144 offset1:152
	ds_read2st64_b32 v[44:45], v199 offset0:32 offset1:40
	s_waitcnt lgkmcnt(0)
	v_pk_fma_f32 v[18:19], v[18:19], v[34:35], v[36:37] op_sel_hi:[1,0,1]
	v_pk_fma_f32 v[2:3], v[2:3], v[34:35], v[38:39] op_sel_hi:[1,0,1]
	ds_read2st64_b32 v[36:37], v199 offset0:160 offset1:168
	ds_read2st64_b32 v[38:39], v199 offset0:48 offset1:56
	v_pk_fma_f32 v[20:21], v[20:21], v[34:35], v[40:41] op_sel_hi:[1,0,1]
	v_pk_fma_f32 v[4:5], v[4:5], v[34:35], v[42:43] op_sel_hi:[1,0,1]
	v_pk_fma_f32 v[22:23], v[22:23], v[34:35], v[44:45] op_sel_hi:[1,0,1]
	s_waitcnt lgkmcnt(0)
	v_pk_fma_f32 v[6:7], v[6:7], v[34:35], v[36:37] op_sel_hi:[1,0,1]
	ds_read2st64_b32 v[36:37], v199 offset0:176 offset1:184
	ds_read2st64_b32 v[40:41], v199 offset0:64 offset1:72
	ds_read2st64_b32 v[42:43], v199 offset0:192 offset1:200
	v_pk_fma_f32 v[24:25], v[24:25], v[34:35], v[38:39] op_sel_hi:[1,0,1]
	ds_read2st64_b32 v[38:39], v199 offset0:80 offset1:88
	s_waitcnt lgkmcnt(0)
	v_pk_fma_f32 v[8:9], v[8:9], v[34:35], v[36:37] op_sel_hi:[1,0,1]
	v_pk_fma_f32 v[26:27], v[26:27], v[34:35], v[40:41] op_sel_hi:[1,0,1]
	v_pk_fma_f32 v[10:11], v[10:11], v[34:35], v[42:43] op_sel_hi:[1,0,1]
	ds_read2st64_b32 v[36:37], v199 offset0:208 offset1:216
	v_pk_fma_f32 v[28:29], v[28:29], v[34:35], v[38:39] op_sel_hi:[1,0,1]
	ds_read2st64_b32 v[38:39], v199 offset0:96 offset1:104
	ds_read2st64_b32 v[40:41], v199 offset0:224 offset1:232
	ds_read2st64_b32 v[42:43], v199 offset0:112 offset1:120
	ds_read2st64_b32 v[44:45], v199 offset0:240 offset1:248
	v_cvt_pk_bf16_f32 v2, v2, v3
	s_waitcnt lgkmcnt(0)
	v_pk_fma_f32 v[30:31], v[30:31], v[34:35], v[38:39] op_sel_hi:[1,0,1]
	v_pk_fma_f32 v[12:13], v[12:13], v[34:35], v[36:37] op_sel_hi:[1,0,1]
	v_pk_fma_f32 v[14:15], v[14:15], v[34:35], v[40:41] op_sel_hi:[1,0,1]
	v_pk_fma_f32 v[32:33], v[32:33], v[34:35], v[42:43] op_sel_hi:[1,0,1]
	v_pk_fma_f32 v[16:17], v[16:17], v[34:35], v[44:45] op_sel_hi:[1,0,1]
	v_lshlrev_b64 v[34:35], 11, v[184:185]
	v_lshl_add_u64 v[34:35], s[94:95], 0, v[34:35]
	v_lshlrev_b32_e32 v36, 1, v183
	v_mov_b32_e32 v37, v0
	v_lshl_add_u64 v[34:35], v[34:35], 0, v[36:37]
	v_mov_b32_e32 v183, v0
	v_lshl_add_u64 v[34:35], v[34:35], 0, v[182:183]
	v_cvt_pk_bf16_f32 v3, v4, v5
	global_store_dwordx2 v[34:35], v[2:3], off offset:64
	v_cvt_pk_bf16_f32 v2, v22, v23
	v_cvt_pk_bf16_f32 v3, v24, v25
	global_store_dwordx2 v[34:35], v[2:3], off offset:16
	v_cvt_pk_bf16_f32 v2, v6, v7
	v_cvt_pk_bf16_f32 v3, v8, v9
	global_store_dwordx2 v[34:35], v[2:3], off offset:80
	v_cvt_pk_bf16_f32 v2, v26, v27
	v_cvt_pk_bf16_f32 v3, v28, v29
	global_store_dwordx2 v[34:35], v[2:3], off offset:32
	v_cvt_pk_bf16_f32 v2, v10, v11
	v_cvt_pk_bf16_f32 v3, v12, v13
	global_store_dwordx2 v[34:35], v[2:3], off offset:96
	v_cvt_pk_bf16_f32 v2, v30, v31
	v_cvt_pk_bf16_f32 v3, v32, v33
	v_readlane_b32 s4, v255, 8
	v_cvt_pk_bf16_f32 v18, v18, v19
	v_cvt_pk_bf16_f32 v19, v20, v21
	global_store_dwordx2 v[34:35], v[2:3], off offset:48
	v_cvt_pk_bf16_f32 v2, v14, v15
	v_cvt_pk_bf16_f32 v3, v16, v17
	v_mov_b32_e32 v1, s4
	global_store_dwordx2 v[34:35], v[18:19], off
	global_store_dwordx2 v[34:35], v[2:3], off offset:112
	s_and_saveexec_b64 s[14:15], s[6:7]
	ds_write_b32 v1, v243
	s_or_b64 exec, exec, s[14:15]
	s_waitcnt lgkmcnt(0)
	s_barrier
	ds_read_b32 v1, v1
	s_movk_i32 s4, 0x400
	s_waitcnt lgkmcnt(0)
	v_cmp_gt_i32_e32 vcc, s4, v1
	v_readfirstlane_b32 s14, v1
	s_cbranch_vccz .LBB0_287
.LBB0_132:
	s_barrier
	s_and_saveexec_b64 s[4:5], s[6:7]
	s_cbranch_execz .LBB0_134
	v_mov_b64_e32 v[2:3], s[28:29]
	s_waitcnt vmcnt(0)
	global_atomic_add v243, v[2:3], v237, off sc0

; __device__ __forceinline__ void attn_phase(unsigned char* ws, LAS unsigned char* lds, const int tid, const int bid, const int l) {
;     ...
;     while (u < 1024) {
;         __syncthreads();
;         if (tid == 0) slot[0] = (int)__hip_atomic_fetch_add(ctr, 1u, __ATOMIC_RELAXED, __HIP_MEMORY_SCOPE_AGENT);
;         int b, g, c;
;         if (u < 384) { g = 1; c = 63 - (u >> 3); b = u & 7; }
;         else if (u < 768) { const int v = u - 384; g = 0; c = 63 - (v >> 3); b = v & 7; }
;         else { const int v = u - 768; c = 15 - (v >> 4); g = (v >> 3) & 1; b = v & 7; }
;         attn_unit(ws, lds, b, g, c, tid);
;         __syncthreads();
;         u = slot[0];
;     }
.LBB0_287:
	s_setprio 0
	v_mov_b32_e32 v243, 0x50
	s_mov_b64 s[4:5], 0
